# P8 final epilogue: write-through (sc1) stores for the output so the end-of-kernel L2 flush is short; stacks on v7
# speedup vs baseline: 1.0036x; 1.0036x over previous
;     __device__ __forceinline__ void operator()(const f32x4 (&acc)[2][2][4][2], const Unit& u, int wr, int wc, int fr, int fq) const {
;     ...
;         for (int ai = 0; ai < 2; ++ai)
; #pragma unroll
;             for (int m = 0; m < 4; ++m) { const size_t off = (size_t)(row0 + ai * HALF + m * 16) * 2048 + col0;
; #pragma unroll
;                 for (int bj = 0; bj < 2; ++bj)
; #pragma unroll
;                     for (int n = 0; n < 2; ++n) { const f32x4 bs = __builtin_nontemporal_load((const f32x4*)(base + off + bj * HALF + n * 16));
;                         *(f32x4*)(out + off + bj * HALF + n * 16) = bs + gv[bj][n] * acc[ai][bj][m][n]; } }
.LBB0_1074:
	s_ashr_i32 s17, s24, 4
	v_lshl_add_u32 v160, s24, 8, v162
	v_lshl_or_b32 v64, s25, 8, v164
	s_mul_hi_i32 s19, s17, 0xc000
	s_mul_i32 s17, s17, 0xc000
	v_ashrrev_i32_e32 v161, 31, v160
	s_add_u32 s26, s40, s17
	v_ashrrev_i32_e32 v65, 31, v64
	v_lshlrev_b64 v[156:157], 13, v[160:161]
	s_addc_u32 s27, s41, s19
	v_lshlrev_b64 v[158:159], 2, v[64:65]
	v_lshl_add_u64 v[156:157], s[66:67], 0, v[156:157]
	v_lshl_add_u64 v[64:65], s[26:27], 0, v[158:159]
	v_lshl_add_u64 v[156:157], v[156:157], 0, v[158:159]
	global_load_dwordx4 v[128:131], v[64:65], off
	global_load_dwordx4 v[116:119], v[64:65], off offset:64
	global_load_dwordx4 v[108:111], v[64:65], off offset:512
	s_nop 0
	global_load_dwordx4 v[64:67], v[64:65], off offset:576
	s_mov_b64 s[24:25], -1
	s_mov_b64 s[98:99], 0x20000
	s_mov_b64 s[100:101], 0xa0000
	v_mov_b64_e32 v[158:159], v[156:157]
	global_load_dwordx4 v[168:171], v[158:159], off nt
	global_load_dwordx4 v[172:175], v[158:159], off offset:64 nt
	global_load_dwordx4 v[176:179], v[158:159], off offset:512 nt
	global_load_dwordx4 v[180:183], v[158:159], off offset:576 nt
	v_lshl_add_u64 v[158:159], v[158:159], 0, s[98:99]
	global_load_dwordx4 v[184:187], v[158:159], off nt
	global_load_dwordx4 v[188:191], v[158:159], off offset:64 nt
	global_load_dwordx4 v[192:195], v[158:159], off offset:512 nt
	global_load_dwordx4 v[196:199], v[158:159], off offset:576 nt
	v_lshl_add_u64 v[158:159], v[158:159], 0, s[98:99]
	global_load_dwordx4 v[200:203], v[158:159], off nt
	global_load_dwordx4 v[204:207], v[158:159], off offset:64 nt
	global_load_dwordx4 v[208:211], v[158:159], off offset:512 nt
	s_waitcnt vmcnt(10)
	v_pk_fma_f32 v[142:143], v[142:143], v[130:131], v[170:171]
	v_pk_fma_f32 v[140:141], v[140:141], v[128:129], v[168:169]
	global_store_dwordx4 v[156:157], v[140:143], off sc1
	global_load_dwordx4 v[168:171], v[158:159], off offset:576 nt
	v_lshl_add_u64 v[158:159], v[158:159], 0, s[98:99]
	s_waitcnt vmcnt(11)
	v_pk_fma_f32 v[138:139], v[138:139], v[118:119], v[174:175]
	v_pk_fma_f32 v[136:137], v[136:137], v[116:117], v[172:173]
	global_store_dwordx4 v[156:157], v[136:139], off offset:64 sc1
	global_load_dwordx4 v[172:175], v[158:159], off nt
	s_waitcnt vmcnt(12)
	v_pk_fma_f32 v[134:135], v[134:135], v[110:111], v[178:179]
	v_pk_fma_f32 v[132:133], v[132:133], v[108:109], v[176:177]
	global_store_dwordx4 v[156:157], v[132:135], off offset:512 sc1
	global_load_dwordx4 v[176:179], v[158:159], off offset:64 nt
	s_waitcnt vmcnt(13)
	v_pk_fma_f32 v[126:127], v[126:127], v[66:67], v[182:183]
	v_pk_fma_f32 v[124:125], v[124:125], v[64:65], v[180:181]
	global_store_dwordx4 v[156:157], v[124:127], off offset:576 sc1
	v_lshl_add_u64 v[156:157], v[156:157], 0, s[98:99]
	global_load_dwordx4 v[180:183], v[158:159], off offset:512 nt
	s_waitcnt vmcnt(14)
	v_pk_fma_f32 v[122:123], v[122:123], v[130:131], v[186:187]
	v_pk_fma_f32 v[120:121], v[120:121], v[128:129], v[184:185]
	global_store_dwordx4 v[156:157], v[120:123], off sc1
	global_load_dwordx4 v[184:187], v[158:159], off offset:576 nt
	v_lshl_add_u64 v[158:159], v[158:159], 0, s[100:101]
	s_waitcnt vmcnt(15)
	v_pk_fma_f32 v[114:115], v[114:115], v[118:119], v[190:191]
	v_pk_fma_f32 v[112:113], v[112:113], v[116:117], v[188:189]
	global_store_dwordx4 v[156:157], v[112:115], off offset:64 sc1
	global_load_dwordx4 v[188:191], v[158:159], off nt
	s_waitcnt vmcnt(16)
	v_pk_fma_f32 v[106:107], v[106:107], v[110:111], v[194:195]
	v_pk_fma_f32 v[104:105], v[104:105], v[108:109], v[192:193]
	global_store_dwordx4 v[156:157], v[104:107], off offset:512 sc1
	global_load_dwordx4 v[192:195], v[158:159], off offset:64 nt
	s_waitcnt vmcnt(17)
	v_pk_fma_f32 v[102:103], v[102:103], v[66:67], v[198:199]
	v_pk_fma_f32 v[100:101], v[100:101], v[64:65], v[196:197]
	global_store_dwordx4 v[156:157], v[100:103], off offset:576 sc1
	v_lshl_add_u64 v[156:157], v[156:157], 0, s[98:99]
	global_load_dwordx4 v[196:199], v[158:159], off offset:512 nt
	s_waitcnt vmcnt(18)
	v_pk_fma_f32 v[98:99], v[98:99], v[130:131], v[202:203]
	v_pk_fma_f32 v[96:97], v[96:97], v[128:129], v[200:201]
	global_store_dwordx4 v[156:157], v[96:99], off sc1
	global_load_dwordx4 v[200:203], v[158:159], off offset:576 nt
	v_lshl_add_u64 v[158:159], v[158:159], 0, s[98:99]
	s_waitcnt vmcnt(19)
	v_pk_fma_f32 v[94:95], v[94:95], v[118:119], v[206:207]
	v_pk_fma_f32 v[92:93], v[92:93], v[116:117], v[204:205]
	global_store_dwordx4 v[156:157], v[92:95], off offset:64 sc1
	global_load_dwordx4 v[204:207], v[158:159], off nt
	s_waitcnt vmcnt(20)
	v_pk_fma_f32 v[90:91], v[90:91], v[110:111], v[210:211]
	v_pk_fma_f32 v[88:89], v[88:89], v[108:109], v[208:209]
	global_store_dwordx4 v[156:157], v[88:91], off offset:512 sc1
	global_load_dwordx4 v[208:211], v[158:159], off offset:64 nt
	s_waitcnt vmcnt(20)
	v_pk_fma_f32 v[86:87], v[86:87], v[66:67], v[170:171]
	v_pk_fma_f32 v[84:85], v[84:85], v[64:65], v[168:169]
	global_store_dwordx4 v[156:157], v[84:87], off offset:576 sc1
	v_lshl_add_u64 v[156:157], v[156:157], 0, s[98:99]
	global_load_dwordx4 v[168:171], v[158:159], off offset:512 nt
	s_waitcnt vmcnt(20)
;     __device__ __forceinline__ void operator()(const f32x4 (&acc)[2][2][4][2], const Unit& u, int wr, int wc, int fr, int fq) const {
;     ...
;         for (int ai = 0; ai < 2; ++ai)
; #pragma unroll
;             for (int m = 0; m < 4; ++m) { const size_t off = (size_t)(row0 + ai * HALF + m * 16) * 2048 + col0;
; #pragma unroll
;                 for (int bj = 0; bj < 2; ++bj)
; #pragma unroll
;                     for (int n = 0; n < 2; ++n) { const f32x4 bs = __builtin_nontemporal_load((const f32x4*)(base + off + bj * HALF + n * 16));
;                         *(f32x4*)(out + off + bj * HALF + n * 16) = bs + gv[bj][n] * acc[ai][bj][m][n]; } }
	v_pk_fma_f32 v[82:83], v[82:83], v[130:131], v[174:175]
	v_pk_fma_f32 v[80:81], v[80:81], v[128:129], v[172:173]
	global_store_dwordx4 v[156:157], v[80:83], off sc1
	global_load_dwordx4 v[172:175], v[158:159], off offset:576 nt
	v_lshl_add_u64 v[158:159], v[158:159], 0, s[98:99]
	s_waitcnt vmcnt(20)
	v_pk_fma_f32 v[78:79], v[78:79], v[118:119], v[178:179]
	v_pk_fma_f32 v[76:77], v[76:77], v[116:117], v[176:177]
	global_store_dwordx4 v[156:157], v[76:79], off offset:64 sc1
	global_load_dwordx4 v[176:179], v[158:159], off nt
	s_waitcnt vmcnt(20)
	v_pk_fma_f32 v[74:75], v[74:75], v[110:111], v[182:183]
	v_pk_fma_f32 v[72:73], v[72:73], v[108:109], v[180:181]
	global_store_dwordx4 v[156:157], v[72:75], off offset:512 sc1
	global_load_dwordx4 v[180:183], v[158:159], off offset:64 nt
	s_waitcnt vmcnt(20)
	v_pk_fma_f32 v[70:71], v[70:71], v[66:67], v[186:187]
	v_pk_fma_f32 v[68:69], v[68:69], v[64:65], v[184:185]
	global_store_dwordx4 v[156:157], v[68:71], off offset:576 sc1
	v_lshl_add_u64 v[156:157], v[156:157], 0, s[100:101]
	global_load_dwordx4 v[184:187], v[158:159], off offset:512 nt
	s_waitcnt vmcnt(20)
	v_pk_fma_f32 v[62:63], v[62:63], v[130:131], v[190:191]
	v_pk_fma_f32 v[60:61], v[60:61], v[128:129], v[188:189]
	global_store_dwordx4 v[156:157], v[60:63], off sc1
	global_load_dwordx4 v[188:191], v[158:159], off offset:576 nt
	v_lshl_add_u64 v[158:159], v[158:159], 0, s[98:99]
	s_waitcnt vmcnt(20)
	v_pk_fma_f32 v[58:59], v[58:59], v[118:119], v[194:195]
	v_pk_fma_f32 v[56:57], v[56:57], v[116:117], v[192:193]
	global_store_dwordx4 v[156:157], v[56:59], off offset:64 sc1
	global_load_dwordx4 v[192:195], v[158:159], off nt
	s_waitcnt vmcnt(20)
	v_pk_fma_f32 v[54:55], v[54:55], v[110:111], v[198:199]
	v_pk_fma_f32 v[52:53], v[52:53], v[108:109], v[196:197]
	global_store_dwordx4 v[156:157], v[52:55], off offset:512 sc1
	global_load_dwordx4 v[196:199], v[158:159], off offset:64 nt
	s_waitcnt vmcnt(20)
	v_pk_fma_f32 v[50:51], v[50:51], v[66:67], v[202:203]
	v_pk_fma_f32 v[48:49], v[48:49], v[64:65], v[200:201]
	global_store_dwordx4 v[156:157], v[48:51], off offset:576 sc1
	v_lshl_add_u64 v[156:157], v[156:157], 0, s[98:99]
	global_load_dwordx4 v[200:203], v[158:159], off offset:512 nt
	s_waitcnt vmcnt(20)
	v_pk_fma_f32 v[46:47], v[46:47], v[130:131], v[206:207]
	v_pk_fma_f32 v[44:45], v[44:45], v[128:129], v[204:205]
	global_store_dwordx4 v[156:157], v[44:47], off sc1
	global_load_dwordx4 v[204:207], v[158:159], off offset:576 nt
	s_waitcnt vmcnt(20)
	v_pk_fma_f32 v[42:43], v[42:43], v[118:119], v[210:211]
	v_pk_fma_f32 v[40:41], v[40:41], v[116:117], v[208:209]
	global_store_dwordx4 v[156:157], v[40:43], off offset:64 sc1
	s_waitcnt vmcnt(19)
	v_pk_fma_f32 v[38:39], v[38:39], v[110:111], v[170:171]
	v_pk_fma_f32 v[36:37], v[36:37], v[108:109], v[168:169]
	global_store_dwordx4 v[156:157], v[36:39], off offset:512 sc1
	s_waitcnt vmcnt(18)
	v_pk_fma_f32 v[34:35], v[34:35], v[66:67], v[174:175]
	v_pk_fma_f32 v[32:33], v[32:33], v[64:65], v[172:173]
	global_store_dwordx4 v[156:157], v[32:35], off offset:576 sc1
	v_lshl_add_u64 v[156:157], v[156:157], 0, s[98:99]
	s_waitcnt vmcnt(17)
	v_pk_fma_f32 v[30:31], v[30:31], v[130:131], v[178:179]
	v_pk_fma_f32 v[28:29], v[28:29], v[128:129], v[176:177]
	global_store_dwordx4 v[156:157], v[28:31], off sc1
	s_waitcnt vmcnt(16)
	v_pk_fma_f32 v[26:27], v[26:27], v[118:119], v[182:183]
	v_pk_fma_f32 v[24:25], v[24:25], v[116:117], v[180:181]
	global_store_dwordx4 v[156:157], v[24:27], off offset:64 sc1
	s_waitcnt vmcnt(15)
	v_pk_fma_f32 v[22:23], v[22:23], v[110:111], v[186:187]
	v_pk_fma_f32 v[20:21], v[20:21], v[108:109], v[184:185]
	global_store_dwordx4 v[156:157], v[20:23], off offset:512 sc1
	s_waitcnt vmcnt(14)
	v_pk_fma_f32 v[18:19], v[18:19], v[66:67], v[190:191]
	v_pk_fma_f32 v[16:17], v[16:17], v[64:65], v[188:189]
	global_store_dwordx4 v[156:157], v[16:19], off offset:576 sc1
	v_lshl_add_u64 v[156:157], v[156:157], 0, s[98:99]
	s_waitcnt vmcnt(13)
	v_pk_fma_f32 v[14:15], v[14:15], v[130:131], v[194:195]
	v_pk_fma_f32 v[12:13], v[12:13], v[128:129], v[192:193]
	global_store_dwordx4 v[156:157], v[12:15], off sc1
	s_waitcnt vmcnt(12)
	v_pk_fma_f32 v[10:11], v[10:11], v[118:119], v[198:199]
	v_pk_fma_f32 v[8:9], v[8:9], v[116:117], v[196:197]
	global_store_dwordx4 v[156:157], v[8:11], off offset:64 sc1
	s_waitcnt vmcnt(11)
	v_pk_fma_f32 v[6:7], v[6:7], v[110:111], v[202:203]
	v_pk_fma_f32 v[4:5], v[4:5], v[108:109], v[200:201]
	global_store_dwordx4 v[156:157], v[4:7], off offset:512 sc1
	s_waitcnt vmcnt(10)
	v_pk_fma_f32 v[2:3], v[2:3], v[66:67], v[206:207]
	v_pk_fma_f32 v[0:1], v[0:1], v[64:65], v[204:205]
	global_store_dwordx4 v[156:157], v[0:3], off offset:576 sc1
	s_andn2_b64 vcc, exec, s[0:1]
	s_cbranch_vccnz .LBB0_1063
	s_andn2_b64 vcc, exec, s[2:3]
	s_cbranch_vccnz .LBB0_1062
	s_barrier
	s_branch .LBB0_1062
